# gate/up: the leading half's tile-end alignment barrier moved two row groups into its epilogue, so its epilogue VALU overlaps the trailing half's last MMA block
# speedup vs baseline: 1.0051x; 1.0001x over previous
.Lpeel_exit_3:
.LBB0_896:
	v_lshl_add_u32 v162, s3, 8, v167
	v_or_b32_e32 v160, 16, v162
	v_or_b32_e32 v158, 32, v162
	v_or_b32_e32 v156, 48, v162
	v_add_u32_e32 v154, 0x80, v162
	v_add_u32_e32 v152, 0x90, v162
	v_add_u32_e32 v150, 0xa0, v162
	v_add_u32_e32 v148, 0xb0, v162
	s_mov_b64 s[4:5], -1
	s_cmp_gt_u32 s2, 11
	v_ashrrev_i32_e32 v163, 31, v162
	v_ashrrev_i32_e32 v161, 31, v160
	v_ashrrev_i32_e32 v159, 31, v158
	v_ashrrev_i32_e32 v157, 31, v156
	v_ashrrev_i32_e32 v155, 31, v154
	v_ashrrev_i32_e32 v153, 31, v152
	v_ashrrev_i32_e32 v151, 31, v150
	v_ashrrev_i32_e32 v149, 31, v148
	s_cbranch_scc1 .LBB0_898
	s_lshl_b32 s2, s2, 10
	s_add_i32 s2, s2, 0
	v_add_u32_e32 v134, s2, v169
	v_add_u32_e32 v135, 0x20ac0, v134
	v_add_u32_e32 v164, 0x20a00, v134
	v_add_u32_e32 v168, 0x208c0, v134
	v_add_u32_e32 v170, 0x20880, v134
	v_add_u32_e32 v172, 0x20840, v134
	v_add_u32_e32 v136, 0x20a80, v134
	v_add_u32_e32 v137, 0x20a40, v134
	v_add_u32_e32 v183, 0x20800, v134
	ds_read_b32 v134, v135
	ds_read_b32 v182, v136
	ds_read_b32 v174, v137
	ds_read_b32 v166, v164
	ds_read_b32 v164, v168
	ds_read_b32 v168, v170
	ds_read_b32 v170, v172
	ds_read_b32 v172, v183
	s_mov_b64 s[4:5], 0

.LBB0_900:
	s_waitcnt lgkmcnt(0)
	v_lshl_or_b32 v136, s35, 7, v173
	v_ashrrev_i32_e32 v137, 31, v136
	v_lshl_add_u64 v[136:137], v[136:137], 1, s[66:67]
	v_mul_f32_e32 v188, 0xbfb8aa3b, v172
	v_mul_f32_e32 v190, v172, v172
	v_rcp_f32_e32 v198, v190
	v_pk_mul_f32 v[200:201], v[130:131], v[188:189] op_sel_hi:[1,0]
	v_pk_mul_f32 v[202:203], v[132:133], v[188:189] op_sel_hi:[1,0]
	v_pk_mul_f32 v[204:205], v[122:123], v[188:189] op_sel_hi:[1,0]
	v_pk_mul_f32 v[206:207], v[124:125], v[188:189] op_sel_hi:[1,0]
	v_exp_f32_e32 v200, v200
	v_exp_f32_e32 v201, v201
	v_exp_f32_e32 v202, v202
	v_exp_f32_e32 v203, v203
	v_exp_f32_e32 v204, v204
	v_exp_f32_e32 v205, v205
	v_exp_f32_e32 v206, v206
	v_exp_f32_e32 v207, v207
	v_pk_mul_f32 v[130:131], v[130:131], v[126:127]
	v_pk_mul_f32 v[132:133], v[132:133], v[128:129]
	v_pk_mul_f32 v[122:123], v[122:123], v[118:119]
	v_pk_mul_f32 v[124:125], v[124:125], v[120:121]
	v_fma_f32 v200, v200, v198, v198
	v_fma_f32 v201, v201, v198, v198
	v_fma_f32 v202, v202, v198, v198
	v_fma_f32 v203, v203, v198, v198
	v_fma_f32 v204, v204, v198, v198
	v_fma_f32 v205, v205, v198, v198
	v_fma_f32 v206, v206, v198, v198
	v_fma_f32 v207, v207, v198, v198
	v_rcp_f32_e32 v200, v200
	v_rcp_f32_e32 v201, v201
	v_rcp_f32_e32 v202, v202
	v_rcp_f32_e32 v203, v203
	v_rcp_f32_e32 v204, v204
	v_rcp_f32_e32 v205, v205
	v_rcp_f32_e32 v206, v206
	v_rcp_f32_e32 v207, v207
	v_mad_u64_u32 v[196:197], s[2:3], v162, s78, v[136:137]
	v_pk_mul_f32 v[130:131], v[130:131], v[200:201]
	v_pk_mul_f32 v[132:133], v[132:133], v[202:203]
	v_pk_mul_f32 v[122:123], v[122:123], v[204:205]
	v_pk_mul_f32 v[124:125], v[124:125], v[206:207]
	v_cvt_pk_bf16_f32 v192, v130, v131
	v_cvt_pk_bf16_f32 v193, v132, v133
	v_cvt_pk_bf16_f32 v194, v122, v123
	v_cvt_pk_bf16_f32 v195, v124, v125
	global_store_dwordx4 v[196:197], v[192:195], off
	v_mul_f32_e32 v188, 0xbfb8aa3b, v170
	v_mul_f32_e32 v190, v170, v170
	v_rcp_f32_e32 v198, v190
	v_pk_mul_f32 v[200:201], v[114:115], v[188:189] op_sel_hi:[1,0]
	v_pk_mul_f32 v[202:203], v[116:117], v[188:189] op_sel_hi:[1,0]
	v_pk_mul_f32 v[204:205], v[106:107], v[188:189] op_sel_hi:[1,0]
	v_pk_mul_f32 v[206:207], v[108:109], v[188:189] op_sel_hi:[1,0]
	v_exp_f32_e32 v200, v200
	v_exp_f32_e32 v201, v201
	v_exp_f32_e32 v202, v202
	v_exp_f32_e32 v203, v203
	v_exp_f32_e32 v204, v204
	v_exp_f32_e32 v205, v205
	v_exp_f32_e32 v206, v206
	v_exp_f32_e32 v207, v207
	v_pk_mul_f32 v[114:115], v[114:115], v[110:111]
	v_pk_mul_f32 v[116:117], v[116:117], v[112:113]
	v_pk_mul_f32 v[106:107], v[106:107], v[102:103]
	v_pk_mul_f32 v[108:109], v[108:109], v[104:105]
	v_fma_f32 v200, v200, v198, v198
	v_fma_f32 v201, v201, v198, v198
	v_fma_f32 v202, v202, v198, v198
	v_fma_f32 v203, v203, v198, v198
	v_fma_f32 v204, v204, v198, v198
	v_fma_f32 v205, v205, v198, v198
	v_fma_f32 v206, v206, v198, v198
	v_fma_f32 v207, v207, v198, v198
	v_rcp_f32_e32 v200, v200
	v_rcp_f32_e32 v201, v201
	v_rcp_f32_e32 v202, v202
	v_rcp_f32_e32 v203, v203
	v_rcp_f32_e32 v204, v204
	v_rcp_f32_e32 v205, v205
	v_rcp_f32_e32 v206, v206
	v_rcp_f32_e32 v207, v207
	v_mad_u64_u32 v[196:197], s[2:3], v160, s78, v[136:137]
	v_pk_mul_f32 v[114:115], v[114:115], v[200:201]
	v_pk_mul_f32 v[116:117], v[116:117], v[202:203]
	v_pk_mul_f32 v[106:107], v[106:107], v[204:205]
	v_pk_mul_f32 v[108:109], v[108:109], v[206:207]
	v_cvt_pk_bf16_f32 v192, v114, v115
	v_cvt_pk_bf16_f32 v193, v116, v117
	v_cvt_pk_bf16_f32 v194, v106, v107
	v_cvt_pk_bf16_f32 v195, v108, v109
	global_store_dwordx4 v[196:197], v[192:195], off
	s_cmp_lg_u64 s[8:9], 0
	s_cbranch_scc0 .Lsw_noalign
	s_barrier
.Lsw_noalign:
	v_mul_f32_e32 v188, 0xbfb8aa3b, v168
	v_mul_f32_e32 v190, v168, v168
	v_rcp_f32_e32 v198, v190
	v_pk_mul_f32 v[200:201], v[98:99], v[188:189] op_sel_hi:[1,0]
	v_pk_mul_f32 v[202:203], v[100:101], v[188:189] op_sel_hi:[1,0]
	v_pk_mul_f32 v[204:205], v[90:91], v[188:189] op_sel_hi:[1,0]
	v_pk_mul_f32 v[206:207], v[92:93], v[188:189] op_sel_hi:[1,0]
	v_exp_f32_e32 v200, v200
	v_exp_f32_e32 v201, v201
	v_exp_f32_e32 v202, v202
	v_exp_f32_e32 v203, v203
	v_exp_f32_e32 v204, v204
	v_exp_f32_e32 v205, v205
	v_exp_f32_e32 v206, v206
	v_exp_f32_e32 v207, v207
	v_pk_mul_f32 v[98:99], v[98:99], v[94:95]
	v_pk_mul_f32 v[100:101], v[100:101], v[96:97]
	v_pk_mul_f32 v[90:91], v[90:91], v[86:87]
	v_pk_mul_f32 v[92:93], v[92:93], v[88:89]
	v_fma_f32 v200, v200, v198, v198
	v_fma_f32 v201, v201, v198, v198
	v_fma_f32 v202, v202, v198, v198
	v_fma_f32 v203, v203, v198, v198
	v_fma_f32 v204, v204, v198, v198
	v_fma_f32 v205, v205, v198, v198
	v_fma_f32 v206, v206, v198, v198
	v_fma_f32 v207, v207, v198, v198
	v_rcp_f32_e32 v200, v200
	v_rcp_f32_e32 v201, v201
	v_rcp_f32_e32 v202, v202
	v_rcp_f32_e32 v203, v203
	v_rcp_f32_e32 v204, v204
	v_rcp_f32_e32 v205, v205
	v_rcp_f32_e32 v206, v206
	v_rcp_f32_e32 v207, v207
	v_mad_u64_u32 v[196:197], s[2:3], v158, s78, v[136:137]
	v_pk_mul_f32 v[98:99], v[98:99], v[200:201]
	v_pk_mul_f32 v[100:101], v[100:101], v[202:203]
	v_pk_mul_f32 v[90:91], v[90:91], v[204:205]
	v_pk_mul_f32 v[92:93], v[92:93], v[206:207]
	v_cvt_pk_bf16_f32 v192, v98, v99
	v_cvt_pk_bf16_f32 v193, v100, v101
	v_cvt_pk_bf16_f32 v194, v90, v91
	v_cvt_pk_bf16_f32 v195, v92, v93
	global_store_dwordx4 v[196:197], v[192:195], off
	v_mul_f32_e32 v188, 0xbfb8aa3b, v164
	v_mul_f32_e32 v190, v164, v164
	v_rcp_f32_e32 v198, v190
	v_pk_mul_f32 v[200:201], v[82:83], v[188:189] op_sel_hi:[1,0]
	v_pk_mul_f32 v[202:203], v[84:85], v[188:189] op_sel_hi:[1,0]
	v_pk_mul_f32 v[204:205], v[74:75], v[188:189] op_sel_hi:[1,0]
	v_pk_mul_f32 v[206:207], v[76:77], v[188:189] op_sel_hi:[1,0]
	v_exp_f32_e32 v200, v200
	v_exp_f32_e32 v201, v201
	v_exp_f32_e32 v202, v202
	v_exp_f32_e32 v203, v203
	v_exp_f32_e32 v204, v204
	v_exp_f32_e32 v205, v205
	v_exp_f32_e32 v206, v206
	v_exp_f32_e32 v207, v207
	v_pk_mul_f32 v[82:83], v[82:83], v[78:79]
	v_pk_mul_f32 v[84:85], v[84:85], v[80:81]
	v_pk_mul_f32 v[74:75], v[74:75], v[70:71]
	v_pk_mul_f32 v[76:77], v[76:77], v[72:73]
	v_fma_f32 v200, v200, v198, v198
	v_fma_f32 v201, v201, v198, v198
	v_fma_f32 v202, v202, v198, v198
	v_fma_f32 v203, v203, v198, v198
	v_fma_f32 v204, v204, v198, v198
	v_fma_f32 v205, v205, v198, v198
	v_fma_f32 v206, v206, v198, v198
	v_fma_f32 v207, v207, v198, v198
	v_rcp_f32_e32 v200, v200
	v_rcp_f32_e32 v201, v201
	v_rcp_f32_e32 v202, v202
	v_rcp_f32_e32 v203, v203
	v_rcp_f32_e32 v204, v204
	v_rcp_f32_e32 v205, v205
	v_rcp_f32_e32 v206, v206
	v_rcp_f32_e32 v207, v207
	v_mad_u64_u32 v[196:197], s[2:3], v156, s78, v[136:137]
	v_pk_mul_f32 v[82:83], v[82:83], v[200:201]
	v_pk_mul_f32 v[84:85], v[84:85], v[202:203]
	v_pk_mul_f32 v[74:75], v[74:75], v[204:205]
	v_pk_mul_f32 v[76:77], v[76:77], v[206:207]
	v_cvt_pk_bf16_f32 v192, v82, v83
	v_cvt_pk_bf16_f32 v193, v84, v85
	v_cvt_pk_bf16_f32 v194, v74, v75
	v_cvt_pk_bf16_f32 v195, v76, v77
	global_store_dwordx4 v[196:197], v[192:195], off
	v_mul_f32_e32 v188, 0xbfb8aa3b, v166
	v_mul_f32_e32 v190, v166, v166
	v_rcp_f32_e32 v198, v190
	v_pk_mul_f32 v[200:201], v[66:67], v[188:189] op_sel_hi:[1,0]
	v_pk_mul_f32 v[202:203], v[68:69], v[188:189] op_sel_hi:[1,0]
	v_pk_mul_f32 v[204:205], v[58:59], v[188:189] op_sel_hi:[1,0]
	v_pk_mul_f32 v[206:207], v[60:61], v[188:189] op_sel_hi:[1,0]
	v_exp_f32_e32 v200, v200
	v_exp_f32_e32 v201, v201
	v_exp_f32_e32 v202, v202
	v_exp_f32_e32 v203, v203
	v_exp_f32_e32 v204, v204
	v_exp_f32_e32 v205, v205
	v_exp_f32_e32 v206, v206
	v_exp_f32_e32 v207, v207
	v_pk_mul_f32 v[66:67], v[66:67], v[62:63]
	v_pk_mul_f32 v[68:69], v[68:69], v[64:65]
	v_pk_mul_f32 v[58:59], v[58:59], v[54:55]
	v_pk_mul_f32 v[60:61], v[60:61], v[56:57]
	v_fma_f32 v200, v200, v198, v198
	v_fma_f32 v201, v201, v198, v198
	v_fma_f32 v202, v202, v198, v198
	v_fma_f32 v203, v203, v198, v198
	v_fma_f32 v204, v204, v198, v198
	v_fma_f32 v205, v205, v198, v198
	v_fma_f32 v206, v206, v198, v198
	v_fma_f32 v207, v207, v198, v198
	v_rcp_f32_e32 v200, v200
	v_rcp_f32_e32 v201, v201
	v_rcp_f32_e32 v202, v202
	v_rcp_f32_e32 v203, v203
	v_rcp_f32_e32 v204, v204
	v_rcp_f32_e32 v205, v205
	v_rcp_f32_e32 v206, v206
	v_rcp_f32_e32 v207, v207
	v_mad_u64_u32 v[196:197], s[2:3], v154, s78, v[136:137]
	v_pk_mul_f32 v[66:67], v[66:67], v[200:201]
	v_pk_mul_f32 v[68:69], v[68:69], v[202:203]
	v_pk_mul_f32 v[58:59], v[58:59], v[204:205]
	v_pk_mul_f32 v[60:61], v[60:61], v[206:207]
	v_cvt_pk_bf16_f32 v192, v66, v67
	v_cvt_pk_bf16_f32 v193, v68, v69
	v_cvt_pk_bf16_f32 v194, v58, v59
	v_cvt_pk_bf16_f32 v195, v60, v61
	global_store_dwordx4 v[196:197], v[192:195], off
	v_mul_f32_e32 v188, 0xbfb8aa3b, v174
	v_mul_f32_e32 v190, v174, v174
	v_rcp_f32_e32 v198, v190
	v_pk_mul_f32 v[200:201], v[50:51], v[188:189] op_sel_hi:[1,0]
	v_pk_mul_f32 v[202:203], v[52:53], v[188:189] op_sel_hi:[1,0]
	v_pk_mul_f32 v[204:205], v[42:43], v[188:189] op_sel_hi:[1,0]
	v_pk_mul_f32 v[206:207], v[44:45], v[188:189] op_sel_hi:[1,0]
	v_exp_f32_e32 v200, v200
	v_exp_f32_e32 v201, v201
	v_exp_f32_e32 v202, v202
	v_exp_f32_e32 v203, v203
	v_exp_f32_e32 v204, v204
	v_exp_f32_e32 v205, v205
	v_exp_f32_e32 v206, v206
	v_exp_f32_e32 v207, v207
	v_pk_mul_f32 v[50:51], v[50:51], v[46:47]
	v_pk_mul_f32 v[52:53], v[52:53], v[48:49]
	v_pk_mul_f32 v[42:43], v[42:43], v[38:39]
	v_pk_mul_f32 v[44:45], v[44:45], v[40:41]
	v_fma_f32 v200, v200, v198, v198
	v_fma_f32 v201, v201, v198, v198
	v_fma_f32 v202, v202, v198, v198
	v_fma_f32 v203, v203, v198, v198
	v_fma_f32 v204, v204, v198, v198
	v_fma_f32 v205, v205, v198, v198
	v_fma_f32 v206, v206, v198, v198
	v_fma_f32 v207, v207, v198, v198
	v_rcp_f32_e32 v200, v200
	v_rcp_f32_e32 v201, v201
	v_rcp_f32_e32 v202, v202
	v_rcp_f32_e32 v203, v203
	v_rcp_f32_e32 v204, v204
	v_rcp_f32_e32 v205, v205
	v_rcp_f32_e32 v206, v206
	v_rcp_f32_e32 v207, v207
	v_mad_u64_u32 v[196:197], s[2:3], v152, s78, v[136:137]
	v_pk_mul_f32 v[50:51], v[50:51], v[200:201]
	v_pk_mul_f32 v[52:53], v[52:53], v[202:203]
	v_pk_mul_f32 v[42:43], v[42:43], v[204:205]
	v_pk_mul_f32 v[44:45], v[44:45], v[206:207]
	v_cvt_pk_bf16_f32 v192, v50, v51
	v_cvt_pk_bf16_f32 v193, v52, v53
	v_cvt_pk_bf16_f32 v194, v42, v43
	v_cvt_pk_bf16_f32 v195, v44, v45
	global_store_dwordx4 v[196:197], v[192:195], off
	v_mul_f32_e32 v188, 0xbfb8aa3b, v182
	v_mul_f32_e32 v190, v182, v182
	v_rcp_f32_e32 v198, v190
	v_pk_mul_f32 v[200:201], v[34:35], v[188:189] op_sel_hi:[1,0]
	v_pk_mul_f32 v[202:203], v[36:37], v[188:189] op_sel_hi:[1,0]
	v_pk_mul_f32 v[204:205], v[26:27], v[188:189] op_sel_hi:[1,0]
	v_pk_mul_f32 v[206:207], v[28:29], v[188:189] op_sel_hi:[1,0]
	v_exp_f32_e32 v200, v200
	v_exp_f32_e32 v201, v201
	v_exp_f32_e32 v202, v202
	v_exp_f32_e32 v203, v203
	v_exp_f32_e32 v204, v204
	v_exp_f32_e32 v205, v205
	v_exp_f32_e32 v206, v206
	v_exp_f32_e32 v207, v207
	v_pk_mul_f32 v[34:35], v[34:35], v[30:31]
	v_pk_mul_f32 v[36:37], v[36:37], v[32:33]
	v_pk_mul_f32 v[26:27], v[26:27], v[22:23]
	v_pk_mul_f32 v[28:29], v[28:29], v[24:25]
	v_fma_f32 v200, v200, v198, v198
	v_fma_f32 v201, v201, v198, v198
	v_fma_f32 v202, v202, v198, v198
	v_fma_f32 v203, v203, v198, v198
	v_fma_f32 v204, v204, v198, v198
	v_fma_f32 v205, v205, v198, v198
	v_fma_f32 v206, v206, v198, v198
	v_fma_f32 v207, v207, v198, v198
	v_rcp_f32_e32 v200, v200
	v_rcp_f32_e32 v201, v201
	v_rcp_f32_e32 v202, v202
	v_rcp_f32_e32 v203, v203
	v_rcp_f32_e32 v204, v204
	v_rcp_f32_e32 v205, v205
	v_rcp_f32_e32 v206, v206
	v_rcp_f32_e32 v207, v207
	v_mad_u64_u32 v[196:197], s[2:3], v150, s78, v[136:137]
	v_pk_mul_f32 v[34:35], v[34:35], v[200:201]
	v_pk_mul_f32 v[36:37], v[36:37], v[202:203]
	v_pk_mul_f32 v[26:27], v[26:27], v[204:205]
	v_pk_mul_f32 v[28:29], v[28:29], v[206:207]
	v_cvt_pk_bf16_f32 v192, v34, v35
	v_cvt_pk_bf16_f32 v193, v36, v37
	v_cvt_pk_bf16_f32 v194, v26, v27
	v_cvt_pk_bf16_f32 v195, v28, v29
	global_store_dwordx4 v[196:197], v[192:195], off
	v_mul_f32_e32 v188, 0xbfb8aa3b, v134
	v_mul_f32_e32 v190, v134, v134
	v_rcp_f32_e32 v198, v190
	v_pk_mul_f32 v[200:201], v[18:19], v[188:189] op_sel_hi:[1,0]
	v_pk_mul_f32 v[202:203], v[20:21], v[188:189] op_sel_hi:[1,0]
	v_pk_mul_f32 v[204:205], v[6:7], v[188:189] op_sel_hi:[1,0]
	v_pk_mul_f32 v[206:207], v[8:9], v[188:189] op_sel_hi:[1,0]
	v_exp_f32_e32 v200, v200
	v_exp_f32_e32 v201, v201
	v_exp_f32_e32 v202, v202
	v_exp_f32_e32 v203, v203
	v_exp_f32_e32 v204, v204
	v_exp_f32_e32 v205, v205
	v_exp_f32_e32 v206, v206
	v_exp_f32_e32 v207, v207
	v_pk_mul_f32 v[18:19], v[18:19], v[10:11]
	v_pk_mul_f32 v[20:21], v[20:21], v[12:13]
	v_pk_mul_f32 v[6:7], v[6:7], v[2:3]
	v_pk_mul_f32 v[8:9], v[8:9], v[4:5]
	v_fma_f32 v200, v200, v198, v198
	v_fma_f32 v201, v201, v198, v198
	v_fma_f32 v202, v202, v198, v198
	v_fma_f32 v203, v203, v198, v198
	v_fma_f32 v204, v204, v198, v198
	v_fma_f32 v205, v205, v198, v198
	v_fma_f32 v206, v206, v198, v198
	v_fma_f32 v207, v207, v198, v198
	v_rcp_f32_e32 v200, v200
	v_rcp_f32_e32 v201, v201
	v_rcp_f32_e32 v202, v202
	v_rcp_f32_e32 v203, v203
	v_rcp_f32_e32 v204, v204
	v_rcp_f32_e32 v205, v205
	v_rcp_f32_e32 v206, v206
	v_rcp_f32_e32 v207, v207
	v_mad_u64_u32 v[196:197], s[2:3], v148, s78, v[136:137]
	v_pk_mul_f32 v[18:19], v[18:19], v[200:201]
	v_pk_mul_f32 v[20:21], v[20:21], v[202:203]
	v_pk_mul_f32 v[6:7], v[6:7], v[204:205]
	v_pk_mul_f32 v[8:9], v[8:9], v[206:207]
	v_cvt_pk_bf16_f32 v192, v18, v19
	v_cvt_pk_bf16_f32 v193, v20, v21
	v_cvt_pk_bf16_f32 v194, v6, v7
	v_cvt_pk_bf16_f32 v195, v8, v9
	global_store_dwordx4 v[196:197], v[192:195], off
	s_mov_b64 s[4:5], -1
	s_andn2_b64 vcc, exec, s[0:1]
	s_cbranch_vccnz .LBB0_889
	s_andn2_b64 vcc, exec, s[6:7]
	s_cbranch_vccnz .LBB0_888
	s_barrier
	s_branch .LBB0_888
